# grid barrier: L1 invalidate issued at arrival (right after the arrival atomic) so its latency overlaps the barrier wait; no invalidate after release
# speedup vs baseline: 1.0108x; 1.0108x over previous
; __device__ __forceinline__ unsigned xb_add(unsigned* p, unsigned v) { return __hip_atomic_fetch_add(p, v, __ATOMIC_RELAXED, __HIP_MEMORY_SCOPE_AGENT); }
; #define GRID_BAR() xcd_barrier(bar)
; #define GRID_BAR() do {} while (0)
; #define BOTH(k) (IN(k) && IN((k) + 1))
; __device__ __forceinline__ void xcd_barrier(const XcdBarrier& b) {
;     asm volatile("s_waitcnt vmcnt(0)" ::: "memory");
;     __syncthreads();
;     if (threadIdx.x == 0) {
;         unsigned* bar = b.bar;
;         __builtin_amdgcn_s_waitcnt(0);
;         unsigned nloc = b.st[0], nx = b.st[1];
;         if (nloc == 0u) { xcd_barrier_complete(bar, b.x, nloc, nx); b.st[0] = nloc; b.st[1] = nx; }
;         const unsigned old = xb_add(&bar[XB_XSUB(b.x)], 1u);
;         const unsigned gen = old / nloc;
;         if (old + 1u == (gen + 1u) * nloc) {
;             __builtin_amdgcn_fence(__ATOMIC_RELEASE, "agent");
;             asm volatile("s_waitcnt vmcnt(0)" ::: "memory");
;             const unsigned og = xb_add(&bar[XB_TOP], 1u);
;             const unsigned tg = og / nx;
;             if (og + 1u == (tg + 1u) * nx) xb_add(&bar[XB_TOPGEN], 1u);
; __global__ void __launch_bounds__(NTHR, 2) fwd_kernel(Args args) {
;     ...
;         if (BOTH(PH_PRO)) GRID_BAR();
.LBB0_120:
	s_waitcnt vmcnt(0)
	s_barrier
	s_and_saveexec_b64 s[4:5], s[84:85]
	s_cbranch_execz .LBB0_172
	s_and_b32 s3, s91, 7
	s_lshl_b32 s3, s3, 7
	s_add_u32 s8, s96, 0x4000
	s_addc_u32 s9, s97, 0
	s_add_u32 s6, s8, s3
	s_addc_u32 s7, s9, 0
	v_mov_b32_e32 v1, 0
	v_mov_b32_e32 v2, 1
	s_mov_b32 s12, 0
	s_waitcnt vmcnt(0) lgkmcnt(0)
	global_atomic_add v3, v1, v2, s[6:7] sc0
	buffer_inv sc1
	s_waitcnt vmcnt(1)
	v_cmp_eq_u32_e32 vcc, 31, v3
	s_cbranch_vccz .Lgb0_poll
	buffer_wbl2 sc1
	s_waitcnt vmcnt(0)
	global_atomic_add v1, v2, s[8:9] offset:1024
	global_atomic_add v1, v2, s[8:9] offset:1152
	global_atomic_add v1, v2, s[8:9] offset:1280
	global_atomic_add v1, v2, s[8:9] offset:1408
	global_atomic_add v1, v2, s[8:9] offset:1536
	global_atomic_add v1, v2, s[8:9] offset:1664
	global_atomic_add v1, v2, s[8:9] offset:1792
	global_atomic_add v1, v2, s[8:9] offset:1920

; __device__ __forceinline__ unsigned xb_ld(unsigned* p)              { return __hip_atomic_load(p, __ATOMIC_RELAXED, __HIP_MEMORY_SCOPE_AGENT); }
; __device__ __forceinline__ unsigned xb_add(unsigned* p, unsigned v) { return __hip_atomic_fetch_add(p, v, __ATOMIC_RELAXED, __HIP_MEMORY_SCOPE_AGENT); }
; #define XB_SPIN(cond, bar) do { unsigned _sp = 0; while (cond) { __builtin_amdgcn_s_sleep(1); \
;     if ((++_sp & 255u) == 0u) { if (xb_ld(&(bar)[XB_TMO])) break; if (_sp > XB_SPIN_CAP) { atomicAdd(&(bar)[XB_TMO], 1u); break; } } } } while (0)
; #define GRID_BAR() xcd_barrier(bar)
; #define GRID_BAR() do {} while (0)
; #define BOTH(k) (IN(k) && IN((k) + 1))
; __device__ __forceinline__ void xcd_barrier(const XcdBarrier& b) {
;     ...
;             else XB_SPIN(xb_ld(&bar[XB_TOPGEN]) == tg, bar);
;             __builtin_amdgcn_fence(__ATOMIC_ACQUIRE, "agent");
;             xb_add(&bar[XB_XGEN(b.x)], 1u);
;             asm volatile("s_waitcnt vmcnt(0)" ::: "memory");
;         } else {
;             XB_SPIN(xb_ld(&bar[XB_XGEN(b.x)]) == gen, bar);
;             __builtin_amdgcn_fence(__ATOMIC_ACQUIRE, "agent");
;             asm volatile("s_waitcnt vmcnt(0)" ::: "memory");
;         }
;     }
;     __syncthreads();
; __global__ void __launch_bounds__(NTHR, 2) fwd_kernel(Args args) {
;     ...
;         if (BOTH(PH_PRO)) GRID_BAR();
.Lgb0_done:
	s_waitcnt vmcnt(0)
.LBB0_172:
	s_or_b64 exec, exec, s[4:5]
	s_waitcnt lgkmcnt(0)
	s_barrier

; __device__ __forceinline__ unsigned xb_add(unsigned* p, unsigned v) { return __hip_atomic_fetch_add(p, v, __ATOMIC_RELAXED, __HIP_MEMORY_SCOPE_AGENT); }
; #define GRID_BAR() xcd_barrier(bar)
; #define GRID_BAR() do {} while (0)
; #define BOTH(k) (IN(k) && IN((k) + 1))
; __device__ __forceinline__ void xcd_barrier(const XcdBarrier& b) {
;     asm volatile("s_waitcnt vmcnt(0)" ::: "memory");
;     __syncthreads();
;     if (threadIdx.x == 0) {
;         unsigned* bar = b.bar;
;         __builtin_amdgcn_s_waitcnt(0);
;         unsigned nloc = b.st[0], nx = b.st[1];
;         if (nloc == 0u) { xcd_barrier_complete(bar, b.x, nloc, nx); b.st[0] = nloc; b.st[1] = nx; }
;         const unsigned old = xb_add(&bar[XB_XSUB(b.x)], 1u);
;         const unsigned gen = old / nloc;
;         if (old + 1u == (gen + 1u) * nloc) {
;             __builtin_amdgcn_fence(__ATOMIC_RELEASE, "agent");
;             asm volatile("s_waitcnt vmcnt(0)" ::: "memory");
;             const unsigned og = xb_add(&bar[XB_TOP], 1u);
;             const unsigned tg = og / nx;
;             if (og + 1u == (tg + 1u) * nx) xb_add(&bar[XB_TOPGEN], 1u);
; __global__ void __launch_bounds__(NTHR, 2) fwd_kernel(Args args) {
;     ...
;         if (BOTH(PH_NORM1)) GRID_BAR();
.LBB0_191:
	s_cmp_gt_i32 s95, 2
	s_cbranch_scc0 .LBB0_245
	s_waitcnt vmcnt(0)
	s_barrier
	s_and_saveexec_b64 s[4:5], s[84:85]
	s_cbranch_execz .LBB0_244
	s_and_b32 s3, s91, 7
	s_lshl_b32 s3, s3, 7
	s_add_u32 s8, s96, 0x4800
	s_addc_u32 s9, s97, 0
	s_add_u32 s6, s8, s3
	s_addc_u32 s7, s9, 0
	v_mov_b32_e32 v1, 0
	v_mov_b32_e32 v2, 1
	s_mov_b32 s10, 0
	s_waitcnt vmcnt(0) lgkmcnt(0)
	global_atomic_add v3, v1, v2, s[6:7] sc0
	buffer_inv sc1
	s_waitcnt vmcnt(1)
	v_cmp_eq_u32_e32 vcc, 31, v3
	s_cbranch_vccz .Lgb1_poll
	buffer_wbl2 sc1
	s_waitcnt vmcnt(0)
	global_atomic_add v1, v2, s[8:9] offset:1024
	global_atomic_add v1, v2, s[8:9] offset:1152
	global_atomic_add v1, v2, s[8:9] offset:1280
	global_atomic_add v1, v2, s[8:9] offset:1408
	global_atomic_add v1, v2, s[8:9] offset:1536
	global_atomic_add v1, v2, s[8:9] offset:1664
	global_atomic_add v1, v2, s[8:9] offset:1792
	global_atomic_add v1, v2, s[8:9] offset:1920

; __device__ __forceinline__ unsigned xb_ld(unsigned* p)              { return __hip_atomic_load(p, __ATOMIC_RELAXED, __HIP_MEMORY_SCOPE_AGENT); }
; __device__ __forceinline__ unsigned xb_add(unsigned* p, unsigned v) { return __hip_atomic_fetch_add(p, v, __ATOMIC_RELAXED, __HIP_MEMORY_SCOPE_AGENT); }
; #define XB_SPIN(cond, bar) do { unsigned _sp = 0; while (cond) { __builtin_amdgcn_s_sleep(1); \
;     if ((++_sp & 255u) == 0u) { if (xb_ld(&(bar)[XB_TMO])) break; if (_sp > XB_SPIN_CAP) { atomicAdd(&(bar)[XB_TMO], 1u); break; } } } } while (0)
; #define GRID_BAR() xcd_barrier(bar)
; #define GRID_BAR() do {} while (0)
; #define BOTH(k) (IN(k) && IN((k) + 1))
; __device__ __forceinline__ void xcd_barrier(const XcdBarrier& b) {
;     ...
;             else XB_SPIN(xb_ld(&bar[XB_TOPGEN]) == tg, bar);
;             __builtin_amdgcn_fence(__ATOMIC_ACQUIRE, "agent");
;             xb_add(&bar[XB_XGEN(b.x)], 1u);
;             asm volatile("s_waitcnt vmcnt(0)" ::: "memory");
;         } else {
;             XB_SPIN(xb_ld(&bar[XB_XGEN(b.x)]) == gen, bar);
;             __builtin_amdgcn_fence(__ATOMIC_ACQUIRE, "agent");
;             asm volatile("s_waitcnt vmcnt(0)" ::: "memory");
;         }
;     }
;     __syncthreads();
; __global__ void __launch_bounds__(NTHR, 2) fwd_kernel(Args args) {
;     ...
;         if (BOTH(PH_NORM1)) GRID_BAR();
.Lgb1_done:
	s_waitcnt vmcnt(0)
.LBB0_244:
	s_or_b64 exec, exec, s[4:5]
	s_waitcnt lgkmcnt(0)
	s_barrier

; __device__ __forceinline__ unsigned xb_add(unsigned* p, unsigned v) { return __hip_atomic_fetch_add(p, v, __ATOMIC_RELAXED, __HIP_MEMORY_SCOPE_AGENT); }
; #define GRID_BAR() xcd_barrier(bar)
; #define GRID_BAR() do {} while (0)
; #define BOTH(k) (IN(k) && IN((k) + 1))
; __device__ __forceinline__ void xcd_barrier(const XcdBarrier& b) {
;     asm volatile("s_waitcnt vmcnt(0)" ::: "memory");
;     __syncthreads();
;     if (threadIdx.x == 0) {
;         unsigned* bar = b.bar;
;         __builtin_amdgcn_s_waitcnt(0);
;         unsigned nloc = b.st[0], nx = b.st[1];
;         if (nloc == 0u) { xcd_barrier_complete(bar, b.x, nloc, nx); b.st[0] = nloc; b.st[1] = nx; }
;         const unsigned old = xb_add(&bar[XB_XSUB(b.x)], 1u);
;         const unsigned gen = old / nloc;
;         if (old + 1u == (gen + 1u) * nloc) {
;             __builtin_amdgcn_fence(__ATOMIC_RELEASE, "agent");
;             asm volatile("s_waitcnt vmcnt(0)" ::: "memory");
;             const unsigned og = xb_add(&bar[XB_TOP], 1u);
;             const unsigned tg = og / nx;
;             if (og + 1u == (tg + 1u) * nx) xb_add(&bar[XB_TOPGEN], 1u);
; __global__ void __launch_bounds__(NTHR, 2) fwd_kernel(Args args) {
;     ...
;         if (BOTH(PH_GEMM_IN)) GRID_BAR();
.LBB0_479:
	s_cmp_lt_i32 s95, 4
	s_cbranch_scc1 .LBB0_533
	s_waitcnt vmcnt(0)
	s_barrier
	s_and_saveexec_b64 s[4:5], s[84:85]
	s_cbranch_execz .LBB0_532
	s_and_b32 s10, s91, 7
	s_lshl_b32 s10, s10, 7
	s_add_u32 s8, s96, 0x5000
	s_addc_u32 s9, s97, 0
	s_add_u32 s6, s8, s10
	s_addc_u32 s7, s9, 0
	v_mov_b32_e32 v1, 0
	v_mov_b32_e32 v2, 1
	s_mov_b32 s11, 0
	s_waitcnt vmcnt(0) lgkmcnt(0)
	global_atomic_add v3, v1, v2, s[6:7] sc0
	buffer_inv sc1
	s_waitcnt vmcnt(1)
	v_cmp_eq_u32_e32 vcc, 31, v3
	s_cbranch_vccz .Lgb2_poll
	buffer_wbl2 sc1
	s_waitcnt vmcnt(0)
	global_atomic_add v1, v2, s[8:9] offset:1024
	global_atomic_add v1, v2, s[8:9] offset:1152
	global_atomic_add v1, v2, s[8:9] offset:1280
	global_atomic_add v1, v2, s[8:9] offset:1408
	global_atomic_add v1, v2, s[8:9] offset:1536
	global_atomic_add v1, v2, s[8:9] offset:1664
	global_atomic_add v1, v2, s[8:9] offset:1792
	global_atomic_add v1, v2, s[8:9] offset:1920

; __device__ __forceinline__ unsigned xb_ld(unsigned* p)              { return __hip_atomic_load(p, __ATOMIC_RELAXED, __HIP_MEMORY_SCOPE_AGENT); }
; __device__ __forceinline__ unsigned xb_add(unsigned* p, unsigned v) { return __hip_atomic_fetch_add(p, v, __ATOMIC_RELAXED, __HIP_MEMORY_SCOPE_AGENT); }
; #define XB_SPIN(cond, bar) do { unsigned _sp = 0; while (cond) { __builtin_amdgcn_s_sleep(1); \
;     if ((++_sp & 255u) == 0u) { if (xb_ld(&(bar)[XB_TMO])) break; if (_sp > XB_SPIN_CAP) { atomicAdd(&(bar)[XB_TMO], 1u); break; } } } } while (0)
; #define GRID_BAR() xcd_barrier(bar)
; #define GRID_BAR() do {} while (0)
; #define BOTH(k) (IN(k) && IN((k) + 1))
; __device__ __forceinline__ void xcd_barrier(const XcdBarrier& b) {
;     ...
;             else XB_SPIN(xb_ld(&bar[XB_TOPGEN]) == tg, bar);
;             __builtin_amdgcn_fence(__ATOMIC_ACQUIRE, "agent");
;             xb_add(&bar[XB_XGEN(b.x)], 1u);
;             asm volatile("s_waitcnt vmcnt(0)" ::: "memory");
;         } else {
;             XB_SPIN(xb_ld(&bar[XB_XGEN(b.x)]) == gen, bar);
;             __builtin_amdgcn_fence(__ATOMIC_ACQUIRE, "agent");
;             asm volatile("s_waitcnt vmcnt(0)" ::: "memory");
;         }
;     }
;     __syncthreads();
; __global__ void __launch_bounds__(NTHR, 2) fwd_kernel(Args args) {
;     ...
;         if (BOTH(PH_GEMM_IN)) GRID_BAR();
.Lgb2_done:
	s_waitcnt vmcnt(0)
.LBB0_532:
	s_or_b64 exec, exec, s[4:5]
	s_waitcnt lgkmcnt(0)
	s_barrier

; __device__ __forceinline__ unsigned xb_add(unsigned* p, unsigned v) { return __hip_atomic_fetch_add(p, v, __ATOMIC_RELAXED, __HIP_MEMORY_SCOPE_AGENT); }
; #define GRID_BAR() xcd_barrier(bar)
; #define GRID_BAR() do {} while (0)
; #define BOTH(k) (IN(k) && IN((k) + 1))
; __device__ __forceinline__ void xcd_barrier(const XcdBarrier& b) {
;     asm volatile("s_waitcnt vmcnt(0)" ::: "memory");
;     __syncthreads();
;     if (threadIdx.x == 0) {
;         unsigned* bar = b.bar;
;         __builtin_amdgcn_s_waitcnt(0);
;         unsigned nloc = b.st[0], nx = b.st[1];
;         if (nloc == 0u) { xcd_barrier_complete(bar, b.x, nloc, nx); b.st[0] = nloc; b.st[1] = nx; }
;         const unsigned old = xb_add(&bar[XB_XSUB(b.x)], 1u);
;         const unsigned gen = old / nloc;
;         if (old + 1u == (gen + 1u) * nloc) {
;             __builtin_amdgcn_fence(__ATOMIC_RELEASE, "agent");
;             asm volatile("s_waitcnt vmcnt(0)" ::: "memory");
;             const unsigned og = xb_add(&bar[XB_TOP], 1u);
;             const unsigned tg = og / nx;
;             if (og + 1u == (tg + 1u) * nx) xb_add(&bar[XB_TOPGEN], 1u);
; __global__ void __launch_bounds__(NTHR, 2) fwd_kernel(Args args) {
;     ...
;         if (BOTH(PH_KV)) GRID_BAR();
.LBB0_563:
	s_cmp_gt_i32 s95, 4
	s_cbranch_scc0 .LBB0_617
	s_waitcnt vmcnt(0)
	s_barrier
	s_and_saveexec_b64 s[4:5], s[84:85]
	s_cbranch_execz .LBB0_616
	s_and_b32 s12, s91, 7
	s_lshl_b32 s12, s12, 7
	s_add_u32 s10, s96, 0x5800
	s_addc_u32 s11, s97, 0
	s_add_u32 s8, s10, s12
	s_addc_u32 s9, s11, 0
	v_mov_b32_e32 v1, 0
	v_mov_b32_e32 v2, 1
	s_mov_b32 s13, 0
	s_waitcnt vmcnt(0) lgkmcnt(0)
	global_atomic_add v3, v1, v2, s[8:9] sc0
	buffer_inv sc1
	s_waitcnt vmcnt(1)
	v_cmp_eq_u32_e32 vcc, 31, v3
	s_cbranch_vccz .Lgb3_poll
	buffer_wbl2 sc1
	s_waitcnt vmcnt(0)
	global_atomic_add v1, v2, s[10:11] offset:1024
	global_atomic_add v1, v2, s[10:11] offset:1152
	global_atomic_add v1, v2, s[10:11] offset:1280
	global_atomic_add v1, v2, s[10:11] offset:1408
	global_atomic_add v1, v2, s[10:11] offset:1536
	global_atomic_add v1, v2, s[10:11] offset:1664
	global_atomic_add v1, v2, s[10:11] offset:1792
	global_atomic_add v1, v2, s[10:11] offset:1920

; __device__ __forceinline__ unsigned xb_ld(unsigned* p)              { return __hip_atomic_load(p, __ATOMIC_RELAXED, __HIP_MEMORY_SCOPE_AGENT); }
; __device__ __forceinline__ unsigned xb_add(unsigned* p, unsigned v) { return __hip_atomic_fetch_add(p, v, __ATOMIC_RELAXED, __HIP_MEMORY_SCOPE_AGENT); }
; #define XB_SPIN(cond, bar) do { unsigned _sp = 0; while (cond) { __builtin_amdgcn_s_sleep(1); \
;     if ((++_sp & 255u) == 0u) { if (xb_ld(&(bar)[XB_TMO])) break; if (_sp > XB_SPIN_CAP) { atomicAdd(&(bar)[XB_TMO], 1u); break; } } } } while (0)
; #define GRID_BAR() xcd_barrier(bar)
; #define GRID_BAR() do {} while (0)
; #define BOTH(k) (IN(k) && IN((k) + 1))
; __device__ __forceinline__ void xcd_barrier(const XcdBarrier& b) {
;     ...
;             else XB_SPIN(xb_ld(&bar[XB_TOPGEN]) == tg, bar);
;             __builtin_amdgcn_fence(__ATOMIC_ACQUIRE, "agent");
;             xb_add(&bar[XB_XGEN(b.x)], 1u);
;             asm volatile("s_waitcnt vmcnt(0)" ::: "memory");
;         } else {
;             XB_SPIN(xb_ld(&bar[XB_XGEN(b.x)]) == gen, bar);
;             __builtin_amdgcn_fence(__ATOMIC_ACQUIRE, "agent");
;             asm volatile("s_waitcnt vmcnt(0)" ::: "memory");
;         }
;     }
;     __syncthreads();
; __global__ void __launch_bounds__(NTHR, 2) fwd_kernel(Args args) {
;     ...
;         if (BOTH(PH_KV)) GRID_BAR();
.Lgb3_done:
	s_waitcnt vmcnt(0)
.LBB0_616:
	s_or_b64 exec, exec, s[4:5]
	s_waitcnt lgkmcnt(0)
	s_barrier

; __device__ __forceinline__ unsigned xb_add(unsigned* p, unsigned v) { return __hip_atomic_fetch_add(p, v, __ATOMIC_RELAXED, __HIP_MEMORY_SCOPE_AGENT); }
; #define GRID_BAR() xcd_barrier(bar)
; #define GRID_BAR() do {} while (0)
; #define BOTH(k) (IN(k) && IN((k) + 1))
; __device__ __forceinline__ void xcd_barrier(const XcdBarrier& b) {
;     asm volatile("s_waitcnt vmcnt(0)" ::: "memory");
;     __syncthreads();
;     if (threadIdx.x == 0) {
;         unsigned* bar = b.bar;
;         __builtin_amdgcn_s_waitcnt(0);
;         unsigned nloc = b.st[0], nx = b.st[1];
;         if (nloc == 0u) { xcd_barrier_complete(bar, b.x, nloc, nx); b.st[0] = nloc; b.st[1] = nx; }
;         const unsigned old = xb_add(&bar[XB_XSUB(b.x)], 1u);
;         const unsigned gen = old / nloc;
;         if (old + 1u == (gen + 1u) * nloc) {
;             __builtin_amdgcn_fence(__ATOMIC_RELEASE, "agent");
;             asm volatile("s_waitcnt vmcnt(0)" ::: "memory");
;             const unsigned og = xb_add(&bar[XB_TOP], 1u);
;             const unsigned tg = og / nx;
;             if (og + 1u == (tg + 1u) * nx) xb_add(&bar[XB_TOPGEN], 1u);
; __global__ void __launch_bounds__(NTHR, 2) fwd_kernel(Args args) {
;     ...
;         if (BOTH(PH_SCAN)) GRID_BAR();
.LBB0_626:
	s_or_b64 exec, exec, s[10:11]
	v_readlane_b32 s84, v255, 2
	v_readlane_b32 s80, v255, 8
	s_mov_b64 s[6:7], 0
	s_and_b64 vcc, exec, s[8:9]
	v_readlane_b32 s85, v255, 3
	v_readlane_b32 s81, v255, 9
	s_cbranch_vccz .LBB0_680
	s_waitcnt vmcnt(0)
	s_barrier
	s_and_saveexec_b64 s[6:7], s[84:85]
	s_cbranch_execz .LBB0_679
	s_and_b32 s12, s91, 7
	s_lshl_b32 s12, s12, 7
	s_add_u32 s10, s96, 0x6000
	s_addc_u32 s11, s97, 0
	s_add_u32 s8, s10, s12
	s_addc_u32 s9, s11, 0
	v_mov_b32_e32 v1, 0
	v_mov_b32_e32 v34, 1
	s_mov_b32 s13, 0
	s_waitcnt vmcnt(0) lgkmcnt(0)
	global_atomic_add v35, v1, v34, s[8:9] sc0
	buffer_inv sc1
	s_waitcnt vmcnt(1)
	v_cmp_eq_u32_e32 vcc, 31, v35
	s_cbranch_vccz .Lgb4_poll
	buffer_wbl2 sc1
	s_waitcnt vmcnt(0)
	global_atomic_add v1, v34, s[10:11] offset:1024
	global_atomic_add v1, v34, s[10:11] offset:1152
	global_atomic_add v1, v34, s[10:11] offset:1280
	global_atomic_add v1, v34, s[10:11] offset:1408
	global_atomic_add v1, v34, s[10:11] offset:1536
	global_atomic_add v1, v34, s[10:11] offset:1664
	global_atomic_add v1, v34, s[10:11] offset:1792
	global_atomic_add v1, v34, s[10:11] offset:1920

; __device__ __forceinline__ unsigned xb_ld(unsigned* p)              { return __hip_atomic_load(p, __ATOMIC_RELAXED, __HIP_MEMORY_SCOPE_AGENT); }
; __device__ __forceinline__ unsigned xb_add(unsigned* p, unsigned v) { return __hip_atomic_fetch_add(p, v, __ATOMIC_RELAXED, __HIP_MEMORY_SCOPE_AGENT); }
; #define XB_SPIN(cond, bar) do { unsigned _sp = 0; while (cond) { __builtin_amdgcn_s_sleep(1); \
;     if ((++_sp & 255u) == 0u) { if (xb_ld(&(bar)[XB_TMO])) break; if (_sp > XB_SPIN_CAP) { atomicAdd(&(bar)[XB_TMO], 1u); break; } } } } while (0)
; #define GRID_BAR() xcd_barrier(bar)
; #define GRID_BAR() do {} while (0)
; #define BOTH(k) (IN(k) && IN((k) + 1))
; __device__ __forceinline__ void xcd_barrier(const XcdBarrier& b) {
;     ...
;             else XB_SPIN(xb_ld(&bar[XB_TOPGEN]) == tg, bar);
;             __builtin_amdgcn_fence(__ATOMIC_ACQUIRE, "agent");
;             xb_add(&bar[XB_XGEN(b.x)], 1u);
;             asm volatile("s_waitcnt vmcnt(0)" ::: "memory");
;         } else {
;             XB_SPIN(xb_ld(&bar[XB_XGEN(b.x)]) == gen, bar);
;             __builtin_amdgcn_fence(__ATOMIC_ACQUIRE, "agent");
;             asm volatile("s_waitcnt vmcnt(0)" ::: "memory");
;         }
;     }
;     __syncthreads();
; __global__ void __launch_bounds__(NTHR, 2) fwd_kernel(Args args) {
;     ...
;         if (BOTH(PH_SCAN)) GRID_BAR();
.Lgb4_done:
	s_waitcnt vmcnt(0)
.LBB0_679:
	s_or_b64 exec, exec, s[6:7]
	s_mov_b64 s[6:7], s[4:5]
	s_waitcnt lgkmcnt(0)
	s_barrier

; __device__ __forceinline__ unsigned xb_add(unsigned* p, unsigned v) { return __hip_atomic_fetch_add(p, v, __ATOMIC_RELAXED, __HIP_MEMORY_SCOPE_AGENT); }
; #define GRID_BAR() xcd_barrier(bar)
; #define GRID_BAR() do {} while (0)
; #define BOTH(k) (IN(k) && IN((k) + 1))
; __device__ __forceinline__ void xcd_barrier(const XcdBarrier& b) {
;     asm volatile("s_waitcnt vmcnt(0)" ::: "memory");
;     __syncthreads();
;     if (threadIdx.x == 0) {
;         unsigned* bar = b.bar;
;         __builtin_amdgcn_s_waitcnt(0);
;         unsigned nloc = b.st[0], nx = b.st[1];
;         if (nloc == 0u) { xcd_barrier_complete(bar, b.x, nloc, nx); b.st[0] = nloc; b.st[1] = nx; }
;         const unsigned old = xb_add(&bar[XB_XSUB(b.x)], 1u);
;         const unsigned gen = old / nloc;
;         if (old + 1u == (gen + 1u) * nloc) {
;             __builtin_amdgcn_fence(__ATOMIC_RELEASE, "agent");
;             asm volatile("s_waitcnt vmcnt(0)" ::: "memory");
;             const unsigned og = xb_add(&bar[XB_TOP], 1u);
;             const unsigned tg = og / nx;
;             if (og + 1u == (tg + 1u) * nx) xb_add(&bar[XB_TOPGEN], 1u);
; __global__ void __launch_bounds__(NTHR, 2) fwd_kernel(Args args) {
;     ...
;         if (BOTH(PH_RETOUT)) GRID_BAR();
.LBB0_696:
.LBB0_697:
	s_cmp_gt_i32 s95, 6
	s_cbranch_scc0 .LBB0_751
	s_waitcnt vmcnt(0)
	s_barrier
	s_and_saveexec_b64 s[4:5], s[84:85]
	s_cbranch_execz .LBB0_750
	s_and_b32 s12, s91, 7
	s_lshl_b32 s12, s12, 7
	s_add_u32 s10, s96, 0x6800
	s_addc_u32 s11, s97, 0
	s_add_u32 s6, s10, s12
	s_addc_u32 s7, s11, 0
	v_mov_b32_e32 v1, 0
	v_mov_b32_e32 v2, 1
	s_mov_b32 s13, 0
	s_waitcnt vmcnt(0) lgkmcnt(0)
	global_atomic_add v3, v1, v2, s[6:7] sc0
	buffer_inv sc1
	s_waitcnt vmcnt(1)
	v_cmp_eq_u32_e32 vcc, 31, v3
	s_cbranch_vccz .Lgb5_poll
	buffer_wbl2 sc1
	s_waitcnt vmcnt(0)
	global_atomic_add v1, v2, s[10:11] offset:1024
	global_atomic_add v1, v2, s[10:11] offset:1152
	global_atomic_add v1, v2, s[10:11] offset:1280
	global_atomic_add v1, v2, s[10:11] offset:1408
	global_atomic_add v1, v2, s[10:11] offset:1536
	global_atomic_add v1, v2, s[10:11] offset:1664
	global_atomic_add v1, v2, s[10:11] offset:1792
	global_atomic_add v1, v2, s[10:11] offset:1920

; __device__ __forceinline__ unsigned xb_ld(unsigned* p)              { return __hip_atomic_load(p, __ATOMIC_RELAXED, __HIP_MEMORY_SCOPE_AGENT); }
; __device__ __forceinline__ unsigned xb_add(unsigned* p, unsigned v) { return __hip_atomic_fetch_add(p, v, __ATOMIC_RELAXED, __HIP_MEMORY_SCOPE_AGENT); }
; #define XB_SPIN(cond, bar) do { unsigned _sp = 0; while (cond) { __builtin_amdgcn_s_sleep(1); \
;     if ((++_sp & 255u) == 0u) { if (xb_ld(&(bar)[XB_TMO])) break; if (_sp > XB_SPIN_CAP) { atomicAdd(&(bar)[XB_TMO], 1u); break; } } } } while (0)
; #define GRID_BAR() xcd_barrier(bar)
; #define GRID_BAR() do {} while (0)
; #define BOTH(k) (IN(k) && IN((k) + 1))
; __device__ __forceinline__ void xcd_barrier(const XcdBarrier& b) {
;     ...
;             else XB_SPIN(xb_ld(&bar[XB_TOPGEN]) == tg, bar);
;             __builtin_amdgcn_fence(__ATOMIC_ACQUIRE, "agent");
;             xb_add(&bar[XB_XGEN(b.x)], 1u);
;             asm volatile("s_waitcnt vmcnt(0)" ::: "memory");
;         } else {
;             XB_SPIN(xb_ld(&bar[XB_XGEN(b.x)]) == gen, bar);
;             __builtin_amdgcn_fence(__ATOMIC_ACQUIRE, "agent");
;             asm volatile("s_waitcnt vmcnt(0)" ::: "memory");
;         }
;     }
;     __syncthreads();
; __global__ void __launch_bounds__(NTHR, 2) fwd_kernel(Args args) {
;     ...
;         if (BOTH(PH_RETOUT)) GRID_BAR();
.Lgb5_done:
	s_waitcnt vmcnt(0)
.LBB0_750:
	s_or_b64 exec, exec, s[4:5]
	s_waitcnt lgkmcnt(0)
	s_barrier

; __device__ __forceinline__ unsigned xb_add(unsigned* p, unsigned v) { return __hip_atomic_fetch_add(p, v, __ATOMIC_RELAXED, __HIP_MEMORY_SCOPE_AGENT); }
; #define GRID_BAR() xcd_barrier(bar)
; #define GRID_BAR() do {} while (0)
; #define BOTH(k) (IN(k) && IN((k) + 1))
; __device__ __forceinline__ void xcd_barrier(const XcdBarrier& b) {
;     asm volatile("s_waitcnt vmcnt(0)" ::: "memory");
;     __syncthreads();
;     if (threadIdx.x == 0) {
;         unsigned* bar = b.bar;
;         __builtin_amdgcn_s_waitcnt(0);
;         unsigned nloc = b.st[0], nx = b.st[1];
;         if (nloc == 0u) { xcd_barrier_complete(bar, b.x, nloc, nx); b.st[0] = nloc; b.st[1] = nx; }
;         const unsigned old = xb_add(&bar[XB_XSUB(b.x)], 1u);
;         const unsigned gen = old / nloc;
;         if (old + 1u == (gen + 1u) * nloc) {
;             __builtin_amdgcn_fence(__ATOMIC_RELEASE, "agent");
;             asm volatile("s_waitcnt vmcnt(0)" ::: "memory");
;             const unsigned og = xb_add(&bar[XB_TOP], 1u);
;             const unsigned tg = og / nx;
;             if (og + 1u == (tg + 1u) * nx) xb_add(&bar[XB_TOPGEN], 1u);
; __global__ void __launch_bounds__(NTHR, 2) fwd_kernel(Args args) {
;     ...
;         if (BOTH(PH_GEMM_OUT)) GRID_BAR();
.LBB0_795:
	s_waitcnt vmcnt(0)
	s_waitcnt lgkmcnt(0)
	s_barrier
	s_and_saveexec_b64 s[4:5], s[84:85]
	s_cbranch_execz .LBB0_847
	s_and_b32 s12, s91, 7
	s_lshl_b32 s12, s12, 7
	s_add_u32 s8, s96, 0x7000
	s_addc_u32 s9, s97, 0
	s_add_u32 s6, s8, s12
	s_addc_u32 s7, s9, 0
	v_mov_b32_e32 v1, 0
	v_mov_b32_e32 v2, 1
	s_mov_b32 s13, 0
	s_waitcnt vmcnt(0) lgkmcnt(0)
	global_atomic_add v3, v1, v2, s[6:7] sc0
	buffer_inv sc1
	s_waitcnt vmcnt(1)
	v_cmp_eq_u32_e32 vcc, 31, v3
	s_cbranch_vccz .Lgb6_poll
	buffer_wbl2 sc1
	s_waitcnt vmcnt(0)
	global_atomic_add v1, v2, s[8:9] offset:1024
	global_atomic_add v1, v2, s[8:9] offset:1152
	global_atomic_add v1, v2, s[8:9] offset:1280
	global_atomic_add v1, v2, s[8:9] offset:1408
	global_atomic_add v1, v2, s[8:9] offset:1536
	global_atomic_add v1, v2, s[8:9] offset:1664
	global_atomic_add v1, v2, s[8:9] offset:1792
	global_atomic_add v1, v2, s[8:9] offset:1920

; __device__ __forceinline__ unsigned xb_ld(unsigned* p)              { return __hip_atomic_load(p, __ATOMIC_RELAXED, __HIP_MEMORY_SCOPE_AGENT); }
; __device__ __forceinline__ unsigned xb_add(unsigned* p, unsigned v) { return __hip_atomic_fetch_add(p, v, __ATOMIC_RELAXED, __HIP_MEMORY_SCOPE_AGENT); }
; #define XB_SPIN(cond, bar) do { unsigned _sp = 0; while (cond) { __builtin_amdgcn_s_sleep(1); \
;     if ((++_sp & 255u) == 0u) { if (xb_ld(&(bar)[XB_TMO])) break; if (_sp > XB_SPIN_CAP) { atomicAdd(&(bar)[XB_TMO], 1u); break; } } } } while (0)
; #define GRID_BAR() xcd_barrier(bar)
; #define GRID_BAR() do {} while (0)
; #define BOTH(k) (IN(k) && IN((k) + 1))
; __device__ __forceinline__ void xcd_barrier(const XcdBarrier& b) {
;     ...
;             else XB_SPIN(xb_ld(&bar[XB_TOPGEN]) == tg, bar);
;             __builtin_amdgcn_fence(__ATOMIC_ACQUIRE, "agent");
;             xb_add(&bar[XB_XGEN(b.x)], 1u);
;             asm volatile("s_waitcnt vmcnt(0)" ::: "memory");
;         } else {
;             XB_SPIN(xb_ld(&bar[XB_XGEN(b.x)]) == gen, bar);
;             __builtin_amdgcn_fence(__ATOMIC_ACQUIRE, "agent");
;             asm volatile("s_waitcnt vmcnt(0)" ::: "memory");
;         }
;     }
;     __syncthreads();
; __global__ void __launch_bounds__(NTHR, 2) fwd_kernel(Args args) {
;     ...
;         if (BOTH(PH_GEMM_OUT)) GRID_BAR();
.Lgb6_done:
	s_waitcnt vmcnt(0)
.LBB0_847:
	s_or_b64 exec, exec, s[4:5]
	s_waitcnt lgkmcnt(0)
	s_barrier

; __device__ __forceinline__ unsigned xb_add(unsigned* p, unsigned v) { return __hip_atomic_fetch_add(p, v, __ATOMIC_RELAXED, __HIP_MEMORY_SCOPE_AGENT); }
; #define GRID_BAR() xcd_barrier(bar)
; #define GRID_BAR() do {} while (0)
; #define BOTH(k) (IN(k) && IN((k) + 1))
; __device__ __forceinline__ void xcd_barrier(const XcdBarrier& b) {
;     asm volatile("s_waitcnt vmcnt(0)" ::: "memory");
;     __syncthreads();
;     if (threadIdx.x == 0) {
;         unsigned* bar = b.bar;
;         __builtin_amdgcn_s_waitcnt(0);
;         unsigned nloc = b.st[0], nx = b.st[1];
;         if (nloc == 0u) { xcd_barrier_complete(bar, b.x, nloc, nx); b.st[0] = nloc; b.st[1] = nx; }
;         const unsigned old = xb_add(&bar[XB_XSUB(b.x)], 1u);
;         const unsigned gen = old / nloc;
;         if (old + 1u == (gen + 1u) * nloc) {
;             __builtin_amdgcn_fence(__ATOMIC_RELEASE, "agent");
;             asm volatile("s_waitcnt vmcnt(0)" ::: "memory");
;             const unsigned og = xb_add(&bar[XB_TOP], 1u);
;             const unsigned tg = og / nx;
;             if (og + 1u == (tg + 1u) * nx) xb_add(&bar[XB_TOPGEN], 1u);
; __global__ void __launch_bounds__(NTHR, 2) fwd_kernel(Args args) {
;     ...
;         if (BOTH(PH_GEMM_UP)) GRID_BAR();
.LBB0_924:
	s_cmp_gt_i32 s95, 9
	s_cbranch_scc0 .LBB0_978
	s_waitcnt vmcnt(0)
	s_barrier
	s_and_saveexec_b64 s[4:5], s[84:85]
	s_cbranch_execz .LBB0_977
	s_and_b32 s3, s91, 7
	s_lshl_b32 s3, s3, 7
	s_add_u32 s8, s96, 0x7800
	s_addc_u32 s9, s97, 0
	s_add_u32 s6, s8, s3
	s_addc_u32 s7, s9, 0
	v_mov_b32_e32 v1, 0
	v_mov_b32_e32 v2, 1
	s_mov_b32 s10, 0
	s_waitcnt vmcnt(0) lgkmcnt(0)
	global_atomic_add v3, v1, v2, s[6:7] sc0
	buffer_inv sc1
	s_waitcnt vmcnt(1)
	v_cmp_eq_u32_e32 vcc, 31, v3
	s_cbranch_vccz .Lgb7_poll
	buffer_wbl2 sc1
	s_waitcnt vmcnt(0)
	global_atomic_add v1, v2, s[8:9] offset:1024
	global_atomic_add v1, v2, s[8:9] offset:1152
	global_atomic_add v1, v2, s[8:9] offset:1280
	global_atomic_add v1, v2, s[8:9] offset:1408
	global_atomic_add v1, v2, s[8:9] offset:1536
	global_atomic_add v1, v2, s[8:9] offset:1664
	global_atomic_add v1, v2, s[8:9] offset:1792
	global_atomic_add v1, v2, s[8:9] offset:1920

; __device__ __forceinline__ unsigned xb_ld(unsigned* p)              { return __hip_atomic_load(p, __ATOMIC_RELAXED, __HIP_MEMORY_SCOPE_AGENT); }
; __device__ __forceinline__ unsigned xb_add(unsigned* p, unsigned v) { return __hip_atomic_fetch_add(p, v, __ATOMIC_RELAXED, __HIP_MEMORY_SCOPE_AGENT); }
; #define XB_SPIN(cond, bar) do { unsigned _sp = 0; while (cond) { __builtin_amdgcn_s_sleep(1); \
;     if ((++_sp & 255u) == 0u) { if (xb_ld(&(bar)[XB_TMO])) break; if (_sp > XB_SPIN_CAP) { atomicAdd(&(bar)[XB_TMO], 1u); break; } } } } while (0)
; #define GRID_BAR() xcd_barrier(bar)
; #define GRID_BAR() do {} while (0)
; #define BOTH(k) (IN(k) && IN((k) + 1))
; __device__ __forceinline__ void xcd_barrier(const XcdBarrier& b) {
;     ...
;             else XB_SPIN(xb_ld(&bar[XB_TOPGEN]) == tg, bar);
;             __builtin_amdgcn_fence(__ATOMIC_ACQUIRE, "agent");
;             xb_add(&bar[XB_XGEN(b.x)], 1u);
;             asm volatile("s_waitcnt vmcnt(0)" ::: "memory");
;         } else {
;             XB_SPIN(xb_ld(&bar[XB_XGEN(b.x)]) == gen, bar);
;             __builtin_amdgcn_fence(__ATOMIC_ACQUIRE, "agent");
;             asm volatile("s_waitcnt vmcnt(0)" ::: "memory");
;         }
;     }
;     __syncthreads();
; __global__ void __launch_bounds__(NTHR, 2) fwd_kernel(Args args) {
;     ...
;         if (BOTH(PH_GEMM_UP)) GRID_BAR();
.Lgb7_done:
	s_waitcnt vmcnt(0)
.LBB0_977:
	s_or_b64 exec, exec, s[4:5]
	s_waitcnt lgkmcnt(0)
	s_barrier

; __device__ __forceinline__ unsigned xb_add(unsigned* p, unsigned v) { return __hip_atomic_fetch_add(p, v, __ATOMIC_RELAXED, __HIP_MEMORY_SCOPE_AGENT); }
; #define GRID_BAR() xcd_barrier(bar)
; #define GRID_BAR() do {} while (0)
; #define BOTH(k) (IN(k) && IN((k) + 1))
; __device__ __forceinline__ void xcd_barrier(const XcdBarrier& b) {
;     asm volatile("s_waitcnt vmcnt(0)" ::: "memory");
;     __syncthreads();
;     if (threadIdx.x == 0) {
;         unsigned* bar = b.bar;
;         __builtin_amdgcn_s_waitcnt(0);
;         unsigned nloc = b.st[0], nx = b.st[1];
;         if (nloc == 0u) { xcd_barrier_complete(bar, b.x, nloc, nx); b.st[0] = nloc; b.st[1] = nx; }
;         const unsigned old = xb_add(&bar[XB_XSUB(b.x)], 1u);
;         const unsigned gen = old / nloc;
;         if (old + 1u == (gen + 1u) * nloc) {
;             __builtin_amdgcn_fence(__ATOMIC_RELEASE, "agent");
;             asm volatile("s_waitcnt vmcnt(0)" ::: "memory");
;             const unsigned og = xb_add(&bar[XB_TOP], 1u);
;             const unsigned tg = og / nx;
;             if (og + 1u == (tg + 1u) * nx) xb_add(&bar[XB_TOPGEN], 1u);
; __global__ void __launch_bounds__(NTHR, 2) fwd_kernel(Args args) {
;     ...
;         if (BOTH(PH_GEMM_DN)) GRID_BAR();
.LBB0_1007:
	s_cmp_lt_i32 s95, 12
	s_cbranch_scc1 .LBB0_1061
	s_waitcnt vmcnt(0)
	s_barrier
	s_and_saveexec_b64 s[2:3], s[84:85]
	s_cbranch_execz .LBB0_1060
	s_and_b32 s8, s91, 7
	s_lshl_b32 s8, s8, 7
	s_add_u32 s6, s96, 0x8000
	s_addc_u32 s7, s97, 0
	s_add_u32 s4, s6, s8
	s_addc_u32 s5, s7, 0
	v_mov_b32_e32 v0, 0
	v_mov_b32_e32 v1, 1
	s_mov_b32 s9, 0
	s_waitcnt vmcnt(0) lgkmcnt(0)
	global_atomic_add v2, v0, v1, s[4:5] sc0
	buffer_inv sc1
	s_waitcnt vmcnt(1)
	v_cmp_eq_u32_e32 vcc, 31, v2
	s_cbranch_vccz .Lgb8_poll
	buffer_wbl2 sc1
	s_waitcnt vmcnt(0)
	global_atomic_add v0, v1, s[6:7] offset:1024
	global_atomic_add v0, v1, s[6:7] offset:1152
	global_atomic_add v0, v1, s[6:7] offset:1280
	global_atomic_add v0, v1, s[6:7] offset:1408
	global_atomic_add v0, v1, s[6:7] offset:1536
	global_atomic_add v0, v1, s[6:7] offset:1664
	global_atomic_add v0, v1, s[6:7] offset:1792
	global_atomic_add v0, v1, s[6:7] offset:1920

; __device__ __forceinline__ unsigned xb_ld(unsigned* p)              { return __hip_atomic_load(p, __ATOMIC_RELAXED, __HIP_MEMORY_SCOPE_AGENT); }
; __device__ __forceinline__ unsigned xb_add(unsigned* p, unsigned v) { return __hip_atomic_fetch_add(p, v, __ATOMIC_RELAXED, __HIP_MEMORY_SCOPE_AGENT); }
; #define XB_SPIN(cond, bar) do { unsigned _sp = 0; while (cond) { __builtin_amdgcn_s_sleep(1); \
;     if ((++_sp & 255u) == 0u) { if (xb_ld(&(bar)[XB_TMO])) break; if (_sp > XB_SPIN_CAP) { atomicAdd(&(bar)[XB_TMO], 1u); break; } } } } while (0)
; #define GRID_BAR() xcd_barrier(bar)
; #define GRID_BAR() do {} while (0)
; #define BOTH(k) (IN(k) && IN((k) + 1))
; __device__ __forceinline__ void xcd_barrier(const XcdBarrier& b) {
;     ...
;             else XB_SPIN(xb_ld(&bar[XB_TOPGEN]) == tg, bar);
;             __builtin_amdgcn_fence(__ATOMIC_ACQUIRE, "agent");
;             xb_add(&bar[XB_XGEN(b.x)], 1u);
;             asm volatile("s_waitcnt vmcnt(0)" ::: "memory");
;         } else {
;             XB_SPIN(xb_ld(&bar[XB_XGEN(b.x)]) == gen, bar);
;             __builtin_amdgcn_fence(__ATOMIC_ACQUIRE, "agent");
;             asm volatile("s_waitcnt vmcnt(0)" ::: "memory");
;         }
;     }
;     __syncthreads();
; __global__ void __launch_bounds__(NTHR, 2) fwd_kernel(Args args) {
;     ...
;         if (BOTH(PH_GEMM_DN)) GRID_BAR();
.Lgb8_done:
	s_waitcnt vmcnt(0)
.LBB0_1060:
	s_or_b64 exec, exec, s[2:3]
	s_waitcnt lgkmcnt(0)
	s_barrier
